# v31
# speedup vs baseline: 1.0068x; 1.0004x over previous
.LBB0_250:
	s_setprio 2
	ds_read_b128 v[24:27], v141
	ds_read_b128 v[28:31], v141 offset:16
	ds_read_b128 v[32:35], v141 offset:256
	ds_read_b128 v[36:39], v141 offset:272
	ds_read_b128 v[40:43], v141 offset:512
	ds_read_b128 v[44:47], v141 offset:528
	ds_read_b128 v[48:51], v141 offset:768
	ds_read_b128 v[52:55], v141 offset:784
	ds_read_b128 v[56:59], v141 offset:1024
	ds_read_b128 v[60:63], v141 offset:1040
	ds_read2_b32 v[134:135], v107 offset0:64 offset1:96
	v_mov_b32_e32 v115, v141
	v_mov_b32_e32 v112, v107
	v_lshlrev_b32_e32 v143, 2, v138
	v_add_u32_e32 v143, 0xe000, v143
	v_add_u32_e32 v148, 0xc000, v114
	v_cndmask_b32_e64 v143, v143, v148, s[6:7]
	s_and_b64 s[40:41], s[38:39], exec
	s_cselect_b32 s40, 0, 0x1f00
	v_add_u32_e32 v143, s40, v143
	s_mul_i32 s85, s36, 0x600
	s_lshl_b32 s86, s36, 8
	s_mov_b32 s73, 0
	s_waitcnt lgkmcnt(0)
	v_pk_mul_f32 v[168:169], v[126:127], v[24:25]
	v_pk_mul_f32 v[170:171], v[118:119], v[24:25]
	s_nop 0
	v_pk_fma_f32 v[168:169], v[128:129], v[26:27], v[168:169]
	v_pk_fma_f32 v[170:171], v[120:121], v[26:27], v[170:171]
	s_nop 0
	v_pk_fma_f32 v[168:169], v[130:131], v[28:29], v[168:169]
	v_pk_fma_f32 v[170:171], v[122:123], v[28:29], v[170:171]
	s_nop 0
	v_pk_fma_f32 v[168:169], v[132:133], v[30:31], v[168:169]
	v_pk_fma_f32 v[170:171], v[124:125], v[30:31], v[170:171]
	s_nop 0
	s_nop 0
	v_add_f32_e32 v168, v168, v169
	v_add_f32_e32 v170, v170, v171
	s_nop 1
	v_add_f32_dpp v168, v168, v168 quad_perm:[1,0,3,2] row_mask:0xf bank_mask:0xf bound_ctrl:1
	v_add_f32_dpp v170, v170, v170 quad_perm:[1,0,3,2] row_mask:0xf bank_mask:0xf bound_ctrl:1
	s_nop 1
	v_add_f32_dpp v168, v168, v168 quad_perm:[2,3,0,1] row_mask:0xf bank_mask:0xf bound_ctrl:1
	v_add_f32_dpp v170, v170, v170 quad_perm:[2,3,0,1] row_mask:0xf bank_mask:0xf bound_ctrl:1
	s_nop 1
	v_sub_f32_dpp v144, -v168, v168 row_half_mirror row_mask:0xf bank_mask:0xf bound_ctrl:1
	v_sub_f32_dpp v146, -v170, v170 row_half_mirror row_mask:0xf bank_mask:0xf bound_ctrl:1
.Lscan_step2:
	s_waitcnt lgkmcnt(1)
	v_add_u32_e32 v115, s85, v115
	v_add_u32_e32 v112, s85, v112
	ds_read_b128 v[64:67], v115
	ds_read_b128 v[68:71], v115 offset:16
	ds_read_b128 v[72:75], v115 offset:256
	ds_read_b128 v[76:79], v115 offset:272
	ds_read_b128 v[80:83], v115 offset:512
	ds_read_b128 v[84:87], v115 offset:528
	ds_read_b128 v[88:91], v115 offset:768
	ds_read_b128 v[92:95], v115 offset:784
	ds_read_b128 v[96:99], v115 offset:1024
	ds_read_b128 v[100:103], v115 offset:1040
	ds_read2_b32 v[136:137], v112 offset0:64 offset1:96
	v_pk_mul_f32 v[148:149], v[40:41], v[144:145] op_sel_hi:[1,0]
	v_pk_mul_f32 v[150:151], v[40:41], v[146:147] op_sel_hi:[1,0]
	v_pk_mul_f32 v[152:153], v[42:43], v[144:145] op_sel_hi:[1,0]
	v_pk_mul_f32 v[154:155], v[42:43], v[146:147] op_sel_hi:[1,0]
	v_pk_mul_f32 v[156:157], v[44:45], v[144:145] op_sel_hi:[1,0]
	v_pk_mul_f32 v[158:159], v[44:45], v[146:147] op_sel_hi:[1,0]
	v_pk_mul_f32 v[160:161], v[46:47], v[144:145] op_sel_hi:[1,0]
	v_pk_mul_f32 v[162:163], v[46:47], v[146:147] op_sel_hi:[1,0]
	v_pk_fma_f32 v[148:149], v[48:49], v[134:135], v[148:149] op_sel_hi:[1,0,1]
	v_pk_fma_f32 v[150:151], v[48:49], v[134:135], v[150:151] op_sel:[0,1,0]
	v_pk_fma_f32 v[152:153], v[50:51], v[134:135], v[152:153] op_sel_hi:[1,0,1]
	v_pk_fma_f32 v[154:155], v[50:51], v[134:135], v[154:155] op_sel:[0,1,0]
	v_pk_fma_f32 v[156:157], v[52:53], v[134:135], v[156:157] op_sel_hi:[1,0,1]
	v_pk_fma_f32 v[158:159], v[52:53], v[134:135], v[158:159] op_sel:[0,1,0]
	v_pk_fma_f32 v[160:161], v[54:55], v[134:135], v[160:161] op_sel_hi:[1,0,1]
	v_pk_fma_f32 v[162:163], v[54:55], v[134:135], v[162:163] op_sel:[0,1,0]
	v_pk_fma_f32 v[126:127], v[126:127], v[32:33], v[148:149]
	v_pk_fma_f32 v[118:119], v[118:119], v[32:33], v[150:151]
	v_pk_fma_f32 v[128:129], v[128:129], v[34:35], v[152:153]
	v_pk_fma_f32 v[120:121], v[120:121], v[34:35], v[154:155]
	v_pk_fma_f32 v[130:131], v[130:131], v[36:37], v[156:157]
	v_pk_fma_f32 v[122:123], v[122:123], v[36:37], v[158:159]
	v_pk_fma_f32 v[132:133], v[132:133], v[38:39], v[160:161]
	v_pk_fma_f32 v[124:125], v[124:125], v[38:39], v[162:163]
	s_waitcnt lgkmcnt(9)
	v_pk_mul_f32 v[164:165], v[126:127], v[56:57]
	v_pk_mul_f32 v[166:167], v[118:119], v[56:57]
	v_pk_mul_f32 v[168:169], v[126:127], v[64:65]
	v_pk_mul_f32 v[170:171], v[118:119], v[64:65]
	v_pk_fma_f32 v[164:165], v[128:129], v[58:59], v[164:165]
	v_pk_fma_f32 v[166:167], v[120:121], v[58:59], v[166:167]
	v_pk_fma_f32 v[168:169], v[128:129], v[66:67], v[168:169]
	v_pk_fma_f32 v[170:171], v[120:121], v[66:67], v[170:171]
	v_pk_fma_f32 v[164:165], v[130:131], v[60:61], v[164:165]
	v_pk_fma_f32 v[166:167], v[122:123], v[60:61], v[166:167]
	v_pk_fma_f32 v[168:169], v[130:131], v[68:69], v[168:169]
	v_pk_fma_f32 v[170:171], v[122:123], v[68:69], v[170:171]
	v_pk_fma_f32 v[164:165], v[132:133], v[62:63], v[164:165]
	v_pk_fma_f32 v[166:167], v[124:125], v[62:63], v[166:167]
	v_pk_fma_f32 v[168:169], v[132:133], v[70:71], v[168:169]
	v_pk_fma_f32 v[170:171], v[124:125], v[70:71], v[170:171]
	v_add_f32_e32 v164, v164, v165
	v_add_f32_e32 v166, v166, v167
	v_add_f32_e32 v168, v168, v169
	v_add_f32_e32 v170, v170, v171
	v_add_f32_dpp v164, v164, v164 quad_perm:[1,0,3,2] row_mask:0xf bank_mask:0xf bound_ctrl:1
	v_add_f32_dpp v166, v166, v166 quad_perm:[1,0,3,2] row_mask:0xf bank_mask:0xf bound_ctrl:1
	v_add_f32_dpp v168, v168, v168 quad_perm:[1,0,3,2] row_mask:0xf bank_mask:0xf bound_ctrl:1
	v_add_f32_dpp v170, v170, v170 quad_perm:[1,0,3,2] row_mask:0xf bank_mask:0xf bound_ctrl:1
	v_add_f32_dpp v164, v164, v164 quad_perm:[2,3,0,1] row_mask:0xf bank_mask:0xf bound_ctrl:1
	v_add_f32_dpp v166, v166, v166 quad_perm:[2,3,0,1] row_mask:0xf bank_mask:0xf bound_ctrl:1
	v_add_f32_dpp v168, v168, v168 quad_perm:[2,3,0,1] row_mask:0xf bank_mask:0xf bound_ctrl:1
	v_add_f32_dpp v170, v170, v170 quad_perm:[2,3,0,1] row_mask:0xf bank_mask:0xf bound_ctrl:1
	v_add_f32_dpp v164, v164, v164 row_half_mirror row_mask:0xf bank_mask:0xf bound_ctrl:1
	v_add_f32_dpp v166, v166, v166 row_half_mirror row_mask:0xf bank_mask:0xf bound_ctrl:1
	v_sub_f32_dpp v144, -v168, v168 row_half_mirror row_mask:0xf bank_mask:0xf bound_ctrl:1
	v_sub_f32_dpp v146, -v170, v170 row_half_mirror row_mask:0xf bank_mask:0xf bound_ctrl:1
	ds_write2_b32 v143, v164, v166 offset1:32
	v_add_u32_e32 v143, s86, v143
	s_cmp_eq_u32 s73, 15
	s_cselect_b32 s50, 0, s85
	s_waitcnt lgkmcnt(1)
	v_add_u32_e32 v115, s50, v115
	v_add_u32_e32 v112, s50, v112
	ds_read_b128 v[24:27], v115
	ds_read_b128 v[28:31], v115 offset:16
	ds_read_b128 v[32:35], v115 offset:256
	ds_read_b128 v[36:39], v115 offset:272
	ds_read_b128 v[40:43], v115 offset:512
	ds_read_b128 v[44:47], v115 offset:528
	ds_read_b128 v[48:51], v115 offset:768
	ds_read_b128 v[52:55], v115 offset:784
	ds_read_b128 v[56:59], v115 offset:1024
	ds_read_b128 v[60:63], v115 offset:1040
	ds_read2_b32 v[134:135], v112 offset0:64 offset1:96
	v_pk_mul_f32 v[148:149], v[80:81], v[144:145] op_sel_hi:[1,0]
	v_pk_mul_f32 v[150:151], v[80:81], v[146:147] op_sel_hi:[1,0]
	v_pk_mul_f32 v[152:153], v[82:83], v[144:145] op_sel_hi:[1,0]
	v_pk_mul_f32 v[154:155], v[82:83], v[146:147] op_sel_hi:[1,0]
	v_pk_mul_f32 v[156:157], v[84:85], v[144:145] op_sel_hi:[1,0]
	v_pk_mul_f32 v[158:159], v[84:85], v[146:147] op_sel_hi:[1,0]
	v_pk_mul_f32 v[160:161], v[86:87], v[144:145] op_sel_hi:[1,0]
	v_pk_mul_f32 v[162:163], v[86:87], v[146:147] op_sel_hi:[1,0]
	v_pk_fma_f32 v[148:149], v[88:89], v[136:137], v[148:149] op_sel_hi:[1,0,1]
	v_pk_fma_f32 v[150:151], v[88:89], v[136:137], v[150:151] op_sel:[0,1,0]
	v_pk_fma_f32 v[152:153], v[90:91], v[136:137], v[152:153] op_sel_hi:[1,0,1]
	v_pk_fma_f32 v[154:155], v[90:91], v[136:137], v[154:155] op_sel:[0,1,0]
	v_pk_fma_f32 v[156:157], v[92:93], v[136:137], v[156:157] op_sel_hi:[1,0,1]
	v_pk_fma_f32 v[158:159], v[92:93], v[136:137], v[158:159] op_sel:[0,1,0]
	v_pk_fma_f32 v[160:161], v[94:95], v[136:137], v[160:161] op_sel_hi:[1,0,1]
	v_pk_fma_f32 v[162:163], v[94:95], v[136:137], v[162:163] op_sel:[0,1,0]
	v_pk_fma_f32 v[126:127], v[126:127], v[72:73], v[148:149]
	v_pk_fma_f32 v[118:119], v[118:119], v[72:73], v[150:151]
	v_pk_fma_f32 v[128:129], v[128:129], v[74:75], v[152:153]
	v_pk_fma_f32 v[120:121], v[120:121], v[74:75], v[154:155]
	v_pk_fma_f32 v[130:131], v[130:131], v[76:77], v[156:157]
	v_pk_fma_f32 v[122:123], v[122:123], v[76:77], v[158:159]
	v_pk_fma_f32 v[132:133], v[132:133], v[78:79], v[160:161]
	v_pk_fma_f32 v[124:125], v[124:125], v[78:79], v[162:163]
	s_waitcnt lgkmcnt(9)
	v_pk_mul_f32 v[164:165], v[126:127], v[96:97]
	v_pk_mul_f32 v[166:167], v[118:119], v[96:97]
	v_pk_mul_f32 v[168:169], v[126:127], v[24:25]
	v_pk_mul_f32 v[170:171], v[118:119], v[24:25]
	v_pk_fma_f32 v[164:165], v[128:129], v[98:99], v[164:165]
	v_pk_fma_f32 v[166:167], v[120:121], v[98:99], v[166:167]
	v_pk_fma_f32 v[168:169], v[128:129], v[26:27], v[168:169]
	v_pk_fma_f32 v[170:171], v[120:121], v[26:27], v[170:171]
	v_pk_fma_f32 v[164:165], v[130:131], v[100:101], v[164:165]
	v_pk_fma_f32 v[166:167], v[122:123], v[100:101], v[166:167]
	v_pk_fma_f32 v[168:169], v[130:131], v[28:29], v[168:169]
	v_pk_fma_f32 v[170:171], v[122:123], v[28:29], v[170:171]
	v_pk_fma_f32 v[164:165], v[132:133], v[102:103], v[164:165]
	v_pk_fma_f32 v[166:167], v[124:125], v[102:103], v[166:167]
	v_pk_fma_f32 v[168:169], v[132:133], v[30:31], v[168:169]
	v_pk_fma_f32 v[170:171], v[124:125], v[30:31], v[170:171]
	v_add_f32_e32 v164, v164, v165
	v_add_f32_e32 v166, v166, v167
	v_add_f32_e32 v168, v168, v169
	v_add_f32_e32 v170, v170, v171
	v_add_f32_dpp v164, v164, v164 quad_perm:[1,0,3,2] row_mask:0xf bank_mask:0xf bound_ctrl:1
	v_add_f32_dpp v166, v166, v166 quad_perm:[1,0,3,2] row_mask:0xf bank_mask:0xf bound_ctrl:1
	v_add_f32_dpp v168, v168, v168 quad_perm:[1,0,3,2] row_mask:0xf bank_mask:0xf bound_ctrl:1
	v_add_f32_dpp v170, v170, v170 quad_perm:[1,0,3,2] row_mask:0xf bank_mask:0xf bound_ctrl:1
	v_add_f32_dpp v164, v164, v164 quad_perm:[2,3,0,1] row_mask:0xf bank_mask:0xf bound_ctrl:1
	v_add_f32_dpp v166, v166, v166 quad_perm:[2,3,0,1] row_mask:0xf bank_mask:0xf bound_ctrl:1
	v_add_f32_dpp v168, v168, v168 quad_perm:[2,3,0,1] row_mask:0xf bank_mask:0xf bound_ctrl:1
	v_add_f32_dpp v170, v170, v170 quad_perm:[2,3,0,1] row_mask:0xf bank_mask:0xf bound_ctrl:1
	v_add_f32_dpp v164, v164, v164 row_half_mirror row_mask:0xf bank_mask:0xf bound_ctrl:1
	v_add_f32_dpp v166, v166, v166 row_half_mirror row_mask:0xf bank_mask:0xf bound_ctrl:1
	v_sub_f32_dpp v144, -v168, v168 row_half_mirror row_mask:0xf bank_mask:0xf bound_ctrl:1
	v_sub_f32_dpp v146, -v170, v170 row_half_mirror row_mask:0xf bank_mask:0xf bound_ctrl:1
	ds_write2_b32 v143, v164, v166 offset1:32
	v_add_u32_e32 v143, s86, v143
	s_add_i32 s73, s73, 1
	s_cmp_lt_u32 s73, 16
	s_cbranch_scc1 .Lscan_step2
	s_setprio 0
	s_branch .LBB0_247
